# deferred-rstd RMSNorm: residual GEMM epilogue also writes bf16(h*gain) and per-row partial sums of squares; norm phase only builds rstd[row] (+ split-K rows); consumer GEMM scales its f32 accumulators
# speedup vs baseline: 1.0508x; 1.0043x over previous
.LBB0_451:
	s_andn2_b64 vcc, exec, s[0:1]
	s_cbranch_vccnz .LBB0_457
	s_cmp_gt_i32 s20, 0x81ff
	s_cbranch_scc1 .LBB0_457
	s_waitcnt lgkmcnt(0)
	v_readlane_b32 s0, v255, 12
	v_readlane_b32 s1, v255, 13
	v_readlane_b32 s34, v251, 49
	v_readlane_b32 s35, v251, 50
	v_lshlrev_b32_e32 v130, 4, v189
	v_lshlrev_b32_e32 v131, 3, v189
	s_nop 1
	global_load_dwordx4 v[48:51], v130, s[0:1]
	global_load_dwordx4 v[52:55], v130, s[0:1] offset:1024
	global_load_dwordx4 v[56:59], v130, s[0:1] offset:2048
	global_load_dwordx4 v[60:63], v130, s[0:1] offset:3072
	s_lshl_b32 s2, s20, 10
	v_add_u32_e32 v132, s2, v130
	v_add_u32_e32 v132, 0x4100000, v132
	global_load_dwordx4 v[138:141], v132, s[68:69]
	s_lshl_b32 s2, s20, 6
	v_lshrrev_b32_e32 v151, 2, v189
	v_lshl_add_u32 v151, v151, 2, s2
	v_add_u32_e32 v151, 0x4308000, v151
	s_mov_b32 s2, 0x11111111
	s_mov_b32 s3, 0x11111111
	s_waitcnt vmcnt(0)
	v_add_f32_e32 v138, v138, v139
	v_add_f32_e32 v140, v140, v141
	v_add_f32_e32 v134, v138, v140
	s_nop 1
	v_add_f32_dpp v134, v134, v134 quad_perm:[1,0,3,2] row_mask:0xf bank_mask:0xf
	s_nop 1
	v_add_f32_dpp v134, v134, v134 quad_perm:[2,3,0,1] row_mask:0xf bank_mask:0xf
	s_nop 0
	v_fmamk_f32 v134, v134, 0x3a800000, v172
	v_rsq_f32_e32 v134, v134
	s_mov_b64 exec, s[2:3]
	global_store_dword v151, v134, s[68:69]
	s_mov_b64 exec, -1
	s_add_u32 s20, s20, 0x8000

.Lnrm_sp_loop:
	s_lshl_b32 s2, s20, 12
	v_add_u32_e32 v132, s2, v130
	global_load_dwordx4 v[0:3], v132, s[72:73] nt
	global_load_dwordx4 v[4:7], v132, s[72:73] offset:1024 nt
	global_load_dwordx4 v[8:11], v132, s[72:73] offset:2048 nt
	global_load_dwordx4 v[12:15], v132, s[72:73] offset:3072 nt
	s_sub_u32 s3, s20, 0x8000
	s_lshl_b32 s3, s3, 12
	v_add_u32_e32 v151, s3, v130
	s_mov_b32 s3, 0x200000
	global_load_dwordx4 v[64:67], v151, s[34:35]
	global_load_dwordx4 v[68:71], v151, s[34:35] offset:1024
	global_load_dwordx4 v[72:75], v151, s[34:35] offset:2048
	global_load_dwordx4 v[76:79], v151, s[34:35] offset:3072
	v_add_u32_e32 v151, s3, v151
	global_load_dwordx4 v[80:83], v151, s[34:35]
	global_load_dwordx4 v[84:87], v151, s[34:35] offset:1024
	global_load_dwordx4 v[88:91], v151, s[34:35] offset:2048
	global_load_dwordx4 v[92:95], v151, s[34:35] offset:3072
	v_add_u32_e32 v151, s3, v151
	global_load_dwordx4 v[96:99], v151, s[34:35]
	global_load_dwordx4 v[100:103], v151, s[34:35] offset:1024
	global_load_dwordx4 v[104:107], v151, s[34:35] offset:2048
	global_load_dwordx4 v[108:111], v151, s[34:35] offset:3072
	v_add_u32_e32 v151, s3, v151
	global_load_dwordx4 v[114:117], v151, s[34:35]
	global_load_dwordx4 v[118:121], v151, s[34:35] offset:1024
	global_load_dwordx4 v[122:125], v151, s[34:35] offset:2048
	global_load_dwordx4 v[126:129], v151, s[34:35] offset:3072
	v_add_u32_e32 v151, s3, v151
	global_load_dwordx4 v[16:19], v151, s[34:35]
	global_load_dwordx4 v[20:23], v151, s[34:35] offset:1024
	global_load_dwordx4 v[24:27], v151, s[34:35] offset:2048
	global_load_dwordx4 v[28:31], v151, s[34:35] offset:3072
	v_add_u32_e32 v151, s3, v151
	global_load_dwordx4 v[32:35], v151, s[34:35]
	global_load_dwordx4 v[36:39], v151, s[34:35] offset:1024
	global_load_dwordx4 v[40:43], v151, s[34:35] offset:2048
	global_load_dwordx4 v[44:47], v151, s[34:35] offset:3072
	v_add_u32_e32 v151, s3, v151
	global_load_dwordx4 v[192:195], v151, s[34:35]
	global_load_dwordx4 v[196:199], v151, s[34:35] offset:1024
	global_load_dwordx4 v[200:203], v151, s[34:35] offset:2048
	global_load_dwordx4 v[204:207], v151, s[34:35] offset:3072
	v_add_u32_e32 v151, s3, v151
	global_load_dwordx4 v[208:211], v151, s[34:35]
	global_load_dwordx4 v[212:215], v151, s[34:35] offset:1024
	global_load_dwordx4 v[216:219], v151, s[34:35] offset:2048
	global_load_dwordx4 v[220:223], v151, s[34:35] offset:3072
	s_waitcnt vmcnt(28)
	v_pk_add_f32 v[0:1], v[0:1], v[64:65]
	v_pk_add_f32 v[2:3], v[2:3], v[66:67]
	v_pk_add_f32 v[4:5], v[4:5], v[68:69]
	v_pk_add_f32 v[6:7], v[6:7], v[70:71]
	v_pk_add_f32 v[8:9], v[8:9], v[72:73]
	v_pk_add_f32 v[10:11], v[10:11], v[74:75]
	v_pk_add_f32 v[12:13], v[12:13], v[76:77]
	v_pk_add_f32 v[14:15], v[14:15], v[78:79]
	s_waitcnt vmcnt(24)
	v_pk_add_f32 v[0:1], v[0:1], v[80:81]
	v_pk_add_f32 v[2:3], v[2:3], v[82:83]
	v_pk_add_f32 v[4:5], v[4:5], v[84:85]
	v_pk_add_f32 v[6:7], v[6:7], v[86:87]
	v_pk_add_f32 v[8:9], v[8:9], v[88:89]
	v_pk_add_f32 v[10:11], v[10:11], v[90:91]
	v_pk_add_f32 v[12:13], v[12:13], v[92:93]
	v_pk_add_f32 v[14:15], v[14:15], v[94:95]
	s_waitcnt vmcnt(20)
	v_pk_add_f32 v[0:1], v[0:1], v[96:97]
	v_pk_add_f32 v[2:3], v[2:3], v[98:99]
	v_pk_add_f32 v[4:5], v[4:5], v[100:101]
	v_pk_add_f32 v[6:7], v[6:7], v[102:103]
	v_pk_add_f32 v[8:9], v[8:9], v[104:105]
	v_pk_add_f32 v[10:11], v[10:11], v[106:107]
	v_pk_add_f32 v[12:13], v[12:13], v[108:109]
	v_pk_add_f32 v[14:15], v[14:15], v[110:111]
	s_waitcnt vmcnt(16)
	v_pk_add_f32 v[0:1], v[0:1], v[114:115]
	v_pk_add_f32 v[2:3], v[2:3], v[116:117]
	v_pk_add_f32 v[4:5], v[4:5], v[118:119]
	v_pk_add_f32 v[6:7], v[6:7], v[120:121]
	v_pk_add_f32 v[8:9], v[8:9], v[122:123]
	v_pk_add_f32 v[10:11], v[10:11], v[124:125]
	v_pk_add_f32 v[12:13], v[12:13], v[126:127]
	v_pk_add_f32 v[14:15], v[14:15], v[128:129]
	s_waitcnt vmcnt(12)
	v_pk_add_f32 v[0:1], v[0:1], v[16:17]
	v_pk_add_f32 v[2:3], v[2:3], v[18:19]
	v_pk_add_f32 v[4:5], v[4:5], v[20:21]
	v_pk_add_f32 v[6:7], v[6:7], v[22:23]
	v_pk_add_f32 v[8:9], v[8:9], v[24:25]
	v_pk_add_f32 v[10:11], v[10:11], v[26:27]
	v_pk_add_f32 v[12:13], v[12:13], v[28:29]
	v_pk_add_f32 v[14:15], v[14:15], v[30:31]
	s_waitcnt vmcnt(8)
	v_pk_add_f32 v[0:1], v[0:1], v[32:33]
	v_pk_add_f32 v[2:3], v[2:3], v[34:35]
	v_pk_add_f32 v[4:5], v[4:5], v[36:37]
	v_pk_add_f32 v[6:7], v[6:7], v[38:39]
	v_pk_add_f32 v[8:9], v[8:9], v[40:41]
	v_pk_add_f32 v[10:11], v[10:11], v[42:43]
	v_pk_add_f32 v[12:13], v[12:13], v[44:45]
	v_pk_add_f32 v[14:15], v[14:15], v[46:47]
	s_waitcnt vmcnt(4)
	v_pk_add_f32 v[0:1], v[0:1], v[192:193]
	v_pk_add_f32 v[2:3], v[2:3], v[194:195]
	v_pk_add_f32 v[4:5], v[4:5], v[196:197]
	v_pk_add_f32 v[6:7], v[6:7], v[198:199]
	v_pk_add_f32 v[8:9], v[8:9], v[200:201]
	v_pk_add_f32 v[10:11], v[10:11], v[202:203]
	v_pk_add_f32 v[12:13], v[12:13], v[204:205]
	v_pk_add_f32 v[14:15], v[14:15], v[206:207]
	s_waitcnt vmcnt(0)
	v_pk_add_f32 v[0:1], v[0:1], v[208:209]
	v_pk_add_f32 v[2:3], v[2:3], v[210:211]
	v_pk_add_f32 v[4:5], v[4:5], v[212:213]
	v_pk_add_f32 v[6:7], v[6:7], v[214:215]
	v_pk_add_f32 v[8:9], v[8:9], v[216:217]
	v_pk_add_f32 v[10:11], v[10:11], v[218:219]
	v_pk_add_f32 v[12:13], v[12:13], v[220:221]
	v_pk_add_f32 v[14:15], v[14:15], v[222:223]
	global_store_dwordx4 v132, v[0:3], s[72:73]
	global_store_dwordx4 v132, v[4:7], s[72:73] offset:1024
	global_store_dwordx4 v132, v[8:11], s[72:73] offset:2048
	global_store_dwordx4 v132, v[12:15], s[72:73] offset:3072
	v_mul_f32_e32 v146, v0, v0
	v_mul_f32_e32 v147, v4, v4
	v_mul_f32_e32 v148, v8, v8
	v_mul_f32_e32 v149, v12, v12
	v_fmac_f32_e32 v146, v1, v1
	v_fmac_f32_e32 v147, v5, v5
	v_fmac_f32_e32 v148, v9, v9
	v_fmac_f32_e32 v149, v13, v13
	v_mul_f32_e32 v138, v2, v2
	v_mul_f32_e32 v139, v6, v6
	v_mul_f32_e32 v140, v10, v10
	v_mul_f32_e32 v141, v14, v14
	v_fmac_f32_e32 v138, v3, v3
	v_fmac_f32_e32 v139, v7, v7
	v_fmac_f32_e32 v140, v11, v11
	v_fmac_f32_e32 v141, v15, v15
	v_add_f32_e32 v146, v146, v138
	v_add_f32_e32 v147, v147, v139
	v_add_f32_e32 v148, v148, v140
	v_add_f32_e32 v149, v149, v141
	v_add_f32_e32 v134, v146, v147
	v_add_f32_e32 v134, v134, v148
	v_add_f32_e32 v134, v134, v149
	s_lshl_b32 s3, s20, 11
	s_nop 0
	v_add_f32_dpp v134, v134, v134 quad_perm:[1,0,3,2] row_mask:0xf bank_mask:0xf
	s_nop 1
	v_add_f32_dpp v134, v134, v134 quad_perm:[2,3,0,1] row_mask:0xf bank_mask:0xf
	s_nop 1
	v_add_f32_dpp v134, v134, v134 row_half_mirror row_mask:0xf bank_mask:0xf
	s_nop 1
	v_add_f32_dpp v134, v134, v134 row_mirror row_mask:0xf bank_mask:0xf
	s_nop 1
	v_add_f32_dpp v134, v134, v134 row_bcast:15 row_mask:0xa bank_mask:0xf
	s_nop 1
	v_add_f32_dpp v134, v134, v134 row_bcast:31 row_mask:0xc bank_mask:0xf
	s_nop 1
	v_readlane_b32 s10, v134, 63
	v_add_u32_e32 v133, s3, v131
	s_lshl_b32 s11, s20, 2
	s_add_u32 s11, s11, 0x4308000
	v_mov_b32_e32 v136, s10
	v_fmamk_f32 v136, v136, 0x3a800000, v172
	v_rsq_f32_e32 v136, v136
	v_mov_b32_e32 v137, s11
	s_nop 0
	global_store_dword v137, v136, s[68:69]
	v_pk_mul_f32 v[0:1], v[0:1], v[48:49]
	v_pk_mul_f32 v[2:3], v[2:3], v[50:51]
	v_pk_mul_f32 v[4:5], v[4:5], v[52:53]
	v_pk_mul_f32 v[6:7], v[6:7], v[54:55]
	v_pk_mul_f32 v[8:9], v[8:9], v[56:57]
	v_pk_mul_f32 v[10:11], v[10:11], v[58:59]
	v_pk_mul_f32 v[12:13], v[12:13], v[60:61]
	v_pk_mul_f32 v[14:15], v[14:15], v[62:63]
	v_cvt_pk_bf16_f32 v138, v0, v1
	v_cvt_pk_bf16_f32 v139, v2, v3
	v_cvt_pk_bf16_f32 v140, v4, v5
	v_cvt_pk_bf16_f32 v141, v6, v7
	v_cvt_pk_bf16_f32 v142, v8, v9
	v_cvt_pk_bf16_f32 v143, v10, v11
	v_cvt_pk_bf16_f32 v144, v12, v13
	v_cvt_pk_bf16_f32 v145, v14, v15
	global_store_dwordx2 v133, v[138:139], s[68:69]
	global_store_dwordx2 v133, v[140:141], s[68:69] offset:512
	global_store_dwordx2 v133, v[142:143], s[68:69] offset:1024
	global_store_dwordx2 v133, v[144:145], s[68:69] offset:1536
	s_add_u32 s20, s20, s4
	s_cmp_gt_i32 s20, 0x81ff
	s_cbranch_scc0 .Lnrm_sp_loop

.LBB0_480:
	s_and_b64 vcc, exec, s[12:13]
	s_cbranch_vccnz .Lres_orig
	v_lshrrev_b32_e32 v145, 6, v154
	v_bfe_u32 v146, v163, 5, 2
	v_lshl_add_u32 v151, s22, 2, v146
	v_lshl_add_u32 v145, v145, 2, v146
	v_mul_u32_u24_e32 v145, 2304, v145
	v_add_u32_e32 v145, 135424, v145
	v_and_b32_e32 v146, 15, v189
	v_mul_u32_u24_e32 v146, 144, v146
	v_lshrrev_b32_e32 v147, 4, v189
	v_lshl_add_u32 v146, v147, 5, v146
	v_add_u32_e32 v152, v145, v146
	v_lshrrev_b32_e32 v146, 3, v189
	v_and_b32_e32 v147, 7, v189
	v_mul_u32_u24_e32 v153, 144, v146
	v_lshl_add_u32 v153, v147, 4, v153
	v_add_u32_e32 v153, v145, v153
	v_and_b32_e32 v148, 0xfffffff0, v154
	v_add_u32_e32 v148, v148, v146
	v_lshl_add_u32 v148, s23, 8, v148
	v_and_b32_e32 v149, 0x60, v163
	v_lshl_add_u32 v149, s22, 8, v149
	v_lshlrev_b32_e32 v238, 6, v148
	v_lshl_add_u32 v238, v151, 2, v238
	v_add_u32_e32 v238, 0x4100000, v238
	v_lshl_add_u32 v150, v147, 2, v149
	v_lshlrev_b32_e32 v239, 11, v148
	v_lshl_add_u32 v239, v150, 1, v239
	v_readlane_b32 s18, v254, 27
	v_readlane_b32 s19, v254, 28
	v_readlane_b32 s20, v254, 33
	v_readlane_b32 s21, v254, 34
	v_lshlrev_b32_e32 v150, 2, v150
	s_cmp_eq_u32 s78, 6
	s_cselect_b64 s[40:41], -1, 0
	s_cmp_eq_u32 s78, 2
	s_cselect_b64 vcc, -1, 0
	s_or_b64 s[40:41], s[40:41], vcc
	s_and_b64 vcc, exec, s[40:41]
	s_cselect_b32 s40, s18, s20
	s_cselect_b32 s41, s19, s21
	global_load_dwordx4 v[224:227], v150, s[40:41]
	global_load_dwordx4 v[228:231], v150, s[40:41] offset:512
	v_lshlrev_b32_e32 v148, 12, v148
	v_lshl_add_u32 v149, v149, 2, v148
	v_lshl_add_u32 v144, v147, 4, v149
	s_mov_b32 s38, 0x01010101
	s_mov_b32 s39, 0x01010101
	v_mov_b32_e32 v145, v144
	v_add_u32_e32 v146, 0x8000, v144
	global_load_dwordx4 v[192:195], v145, s[72:73]
	global_load_dwordx4 v[196:199], v146, s[72:73]
	v_add_u32_e32 v147, 0x200, v144
	v_add_u32_e32 v148, 0x8200, v144
	global_load_dwordx4 v[200:203], v147, s[72:73]
	global_load_dwordx4 v[204:207], v148, s[72:73]
	v_add_u32_e32 v149, 0x10000, v144
	v_add_u32_e32 v150, 0x18000, v144
	global_load_dwordx4 v[208:211], v149, s[72:73]
	global_load_dwordx4 v[212:215], v150, s[72:73]
	v_add_u32_e32 v145, 0x10200, v144
	v_add_u32_e32 v146, 0x18200, v144
	global_load_dwordx4 v[216:219], v145, s[72:73]
	global_load_dwordx4 v[220:223], v146, s[72:73]
	ds_write_b128 v152, v[126:129]
	ds_write_b128 v152, v[122:125] offset:16
	ds_read_b128 v[240:243], v153
	ds_read_b128 v[244:247], v153 offset:1152
	ds_write_b128 v152, v[118:121]
	ds_write_b128 v152, v[114:117] offset:16
	ds_read_b128 v[130:133], v153
	ds_read_b128 v[176:179], v153 offset:1152
	s_waitcnt lgkmcnt(4)
	s_waitcnt vmcnt(6)
	v_pk_add_f32 v[240:241], v[240:241], v[192:193]
	v_pk_add_f32 v[242:243], v[242:243], v[194:195]
	v_pk_add_f32 v[244:245], v[244:245], v[196:197]
	v_pk_add_f32 v[246:247], v[246:247], v[198:199]
	v_mov_b32_e32 v180, v144
	v_add_u32_e32 v181, 0x8000, v144
	global_store_dwordx4 v180, v[240:243], s[72:73]
	global_store_dwordx4 v181, v[244:247], s[72:73]
	v_mul_f32_e32 v232, v240, v240
	v_fmac_f32_e32 v232, v241, v241
	v_fmac_f32_e32 v232, v242, v242
	v_fmac_f32_e32 v232, v243, v243
	v_mul_f32_e32 v233, v244, v244
	v_fmac_f32_e32 v233, v245, v245
	v_fmac_f32_e32 v233, v246, v246
	v_fmac_f32_e32 v233, v247, v247
	v_pk_mul_f32 v[248:249], v[240:241], v[224:225]
	v_pk_mul_f32 v[242:243], v[242:243], v[226:227]
	v_cvt_pk_bf16_f32 v234, v248, v249
	v_cvt_pk_bf16_f32 v235, v242, v243
	v_pk_mul_f32 v[248:249], v[244:245], v[224:225]
	v_pk_mul_f32 v[246:247], v[246:247], v[226:227]
	v_cvt_pk_bf16_f32 v236, v248, v249
	v_cvt_pk_bf16_f32 v237, v246, v247
	v_mov_b32_e32 v170, v239
	v_add_u32_e32 v171, 0x4000, v239
	global_store_dwordx2 v170, v[234:235], s[68:69]
	global_store_dwordx2 v171, v[236:237], s[68:69]
	v_add_u32_e32 v147, 0x20000, v144
	v_add_u32_e32 v148, 0x28000, v144
	global_load_dwordx4 v[192:195], v147, s[72:73]
	global_load_dwordx4 v[196:199], v148, s[72:73]
	ds_write_b128 v152, v[108:111]
	ds_write_b128 v152, v[104:107] offset:16
	ds_read_b128 v[240:243], v153
	ds_read_b128 v[244:247], v153 offset:1152
	s_waitcnt lgkmcnt(4)
	s_waitcnt vmcnt(10)
	v_pk_add_f32 v[130:131], v[130:131], v[200:201]
	v_pk_add_f32 v[132:133], v[132:133], v[202:203]
	v_pk_add_f32 v[176:177], v[176:177], v[204:205]
	v_pk_add_f32 v[178:179], v[178:179], v[206:207]
	v_add_u32_e32 v180, 0x200, v144
	v_add_u32_e32 v181, 0x8200, v144
	global_store_dwordx4 v180, v[130:133], s[72:73]
	global_store_dwordx4 v181, v[176:179], s[72:73]
	v_fmac_f32_e32 v232, v130, v130
	v_fmac_f32_e32 v232, v131, v131
	v_fmac_f32_e32 v232, v132, v132
	v_fmac_f32_e32 v232, v133, v133
	v_fmac_f32_e32 v233, v176, v176
	v_fmac_f32_e32 v233, v177, v177
	v_fmac_f32_e32 v233, v178, v178
	v_fmac_f32_e32 v233, v179, v179
	v_pk_mul_f32 v[248:249], v[130:131], v[228:229]
	v_pk_mul_f32 v[132:133], v[132:133], v[230:231]
	v_cvt_pk_bf16_f32 v234, v248, v249
	v_cvt_pk_bf16_f32 v235, v132, v133
	v_pk_mul_f32 v[248:249], v[176:177], v[228:229]
	v_pk_mul_f32 v[178:179], v[178:179], v[230:231]
	v_cvt_pk_bf16_f32 v236, v248, v249
	v_cvt_pk_bf16_f32 v237, v178, v179
	v_add_u32_e32 v170, 0x100, v239
	v_add_u32_e32 v171, 0x4100, v239
	global_store_dwordx2 v170, v[234:235], s[68:69]
	global_store_dwordx2 v171, v[236:237], s[68:69]
	s_nop 0
	v_add_f32_dpp v232, v232, v232 quad_perm:[1,0,3,2] row_mask:0xf bank_mask:0xf
	v_add_f32_dpp v233, v233, v233 quad_perm:[1,0,3,2] row_mask:0xf bank_mask:0xf
	s_nop 0
	v_add_f32_dpp v232, v232, v232 quad_perm:[2,3,0,1] row_mask:0xf bank_mask:0xf
	v_add_f32_dpp v233, v233, v233 quad_perm:[2,3,0,1] row_mask:0xf bank_mask:0xf
	s_nop 0
	v_add_f32_dpp v232, v232, v232 row_half_mirror row_mask:0xf bank_mask:0xf
	v_add_f32_dpp v233, v233, v233 row_half_mirror row_mask:0xf bank_mask:0xf
	s_nop 0
	v_mov_b32_e32 v151, v238
	s_mov_b64 exec, s[38:39]
	global_store_dword v151, v232, s[68:69]
	global_store_dword v151, v233, s[68:69] offset:512
	s_mov_b64 exec, -1
	v_add_u32_e32 v149, 0x20200, v144
	v_add_u32_e32 v150, 0x28200, v144
	global_load_dwordx4 v[200:203], v149, s[72:73]
	global_load_dwordx4 v[204:207], v150, s[72:73]
	ds_write_b128 v152, v[100:103]
	ds_write_b128 v152, v[96:99] offset:16
	ds_read_b128 v[130:133], v153
	ds_read_b128 v[176:179], v153 offset:1152
	s_waitcnt lgkmcnt(4)
	s_waitcnt vmcnt(16)
	v_pk_add_f32 v[240:241], v[240:241], v[208:209]
	v_pk_add_f32 v[242:243], v[242:243], v[210:211]
	v_pk_add_f32 v[244:245], v[244:245], v[212:213]
	v_pk_add_f32 v[246:247], v[246:247], v[214:215]
	v_add_u32_e32 v180, 0x10000, v144
	v_add_u32_e32 v181, 0x18000, v144
	global_store_dwordx4 v180, v[240:243], s[72:73]
	global_store_dwordx4 v181, v[244:247], s[72:73]
	v_mul_f32_e32 v232, v240, v240
	v_fmac_f32_e32 v232, v241, v241
	v_fmac_f32_e32 v232, v242, v242
	v_fmac_f32_e32 v232, v243, v243
	v_mul_f32_e32 v233, v244, v244
	v_fmac_f32_e32 v233, v245, v245
	v_fmac_f32_e32 v233, v246, v246
	v_fmac_f32_e32 v233, v247, v247
	v_pk_mul_f32 v[248:249], v[240:241], v[224:225]
	v_pk_mul_f32 v[242:243], v[242:243], v[226:227]
	v_cvt_pk_bf16_f32 v234, v248, v249
	v_cvt_pk_bf16_f32 v235, v242, v243
	v_pk_mul_f32 v[248:249], v[244:245], v[224:225]
	v_pk_mul_f32 v[246:247], v[246:247], v[226:227]
	v_cvt_pk_bf16_f32 v236, v248, v249
	v_cvt_pk_bf16_f32 v237, v246, v247
	v_add_u32_e32 v170, 0x8000, v239
	v_add_u32_e32 v171, 0xc000, v239
	global_store_dwordx2 v170, v[234:235], s[68:69]
	global_store_dwordx2 v171, v[236:237], s[68:69]
	v_add_u32_e32 v145, 0x30000, v144
	v_add_u32_e32 v146, 0x38000, v144
	global_load_dwordx4 v[208:211], v145, s[72:73]
	global_load_dwordx4 v[212:215], v146, s[72:73]
	ds_write_b128 v152, v[92:95]
	ds_write_b128 v152, v[88:91] offset:16
	ds_read_b128 v[240:243], v153
	ds_read_b128 v[244:247], v153 offset:1152
	s_waitcnt lgkmcnt(4)
	s_waitcnt vmcnt(20)
	v_pk_add_f32 v[130:131], v[130:131], v[216:217]
	v_pk_add_f32 v[132:133], v[132:133], v[218:219]
	v_pk_add_f32 v[176:177], v[176:177], v[220:221]
	v_pk_add_f32 v[178:179], v[178:179], v[222:223]
	v_add_u32_e32 v180, 0x10200, v144
	v_add_u32_e32 v181, 0x18200, v144
	global_store_dwordx4 v180, v[130:133], s[72:73]
	global_store_dwordx4 v181, v[176:179], s[72:73]
	v_fmac_f32_e32 v232, v130, v130
	v_fmac_f32_e32 v232, v131, v131
	v_fmac_f32_e32 v232, v132, v132
	v_fmac_f32_e32 v232, v133, v133
	v_fmac_f32_e32 v233, v176, v176
	v_fmac_f32_e32 v233, v177, v177
	v_fmac_f32_e32 v233, v178, v178
	v_fmac_f32_e32 v233, v179, v179
	v_pk_mul_f32 v[248:249], v[130:131], v[228:229]
	v_pk_mul_f32 v[132:133], v[132:133], v[230:231]
	v_cvt_pk_bf16_f32 v234, v248, v249
	v_cvt_pk_bf16_f32 v235, v132, v133
	v_pk_mul_f32 v[248:249], v[176:177], v[228:229]
	v_pk_mul_f32 v[178:179], v[178:179], v[230:231]
	v_cvt_pk_bf16_f32 v236, v248, v249
	v_cvt_pk_bf16_f32 v237, v178, v179
	v_add_u32_e32 v170, 0x8100, v239
	v_add_u32_e32 v171, 0xc100, v239
	global_store_dwordx2 v170, v[234:235], s[68:69]
	global_store_dwordx2 v171, v[236:237], s[68:69]
	s_nop 0
	v_add_f32_dpp v232, v232, v232 quad_perm:[1,0,3,2] row_mask:0xf bank_mask:0xf
	v_add_f32_dpp v233, v233, v233 quad_perm:[1,0,3,2] row_mask:0xf bank_mask:0xf
	s_nop 0
	v_add_f32_dpp v232, v232, v232 quad_perm:[2,3,0,1] row_mask:0xf bank_mask:0xf
	v_add_f32_dpp v233, v233, v233 quad_perm:[2,3,0,1] row_mask:0xf bank_mask:0xf
	s_nop 0
	v_add_f32_dpp v232, v232, v232 row_half_mirror row_mask:0xf bank_mask:0xf
	v_add_f32_dpp v233, v233, v233 row_half_mirror row_mask:0xf bank_mask:0xf
	s_nop 0
	v_add_u32_e32 v151, 0x400, v238
	s_mov_b64 exec, s[38:39]
	global_store_dword v151, v232, s[68:69]
	global_store_dword v151, v233, s[68:69] offset:512
	s_mov_b64 exec, -1
	v_add_u32_e32 v147, 0x30200, v144
	v_add_u32_e32 v148, 0x38200, v144
	global_load_dwordx4 v[216:219], v147, s[72:73]
	global_load_dwordx4 v[220:223], v148, s[72:73]
	ds_write_b128 v152, v[84:87]
	ds_write_b128 v152, v[80:83] offset:16
	ds_read_b128 v[130:133], v153
	ds_read_b128 v[176:179], v153 offset:1152
	s_waitcnt lgkmcnt(4)
	s_waitcnt vmcnt(22)
	v_pk_add_f32 v[240:241], v[240:241], v[192:193]
	v_pk_add_f32 v[242:243], v[242:243], v[194:195]
	v_pk_add_f32 v[244:245], v[244:245], v[196:197]
	v_pk_add_f32 v[246:247], v[246:247], v[198:199]
	v_add_u32_e32 v180, 0x20000, v144
	v_add_u32_e32 v181, 0x28000, v144
	global_store_dwordx4 v180, v[240:243], s[72:73]
	global_store_dwordx4 v181, v[244:247], s[72:73]
	v_mul_f32_e32 v232, v240, v240
	v_fmac_f32_e32 v232, v241, v241
	v_fmac_f32_e32 v232, v242, v242
	v_fmac_f32_e32 v232, v243, v243
	v_mul_f32_e32 v233, v244, v244
	v_fmac_f32_e32 v233, v245, v245
	v_fmac_f32_e32 v233, v246, v246
	v_fmac_f32_e32 v233, v247, v247
	v_pk_mul_f32 v[248:249], v[240:241], v[224:225]
	v_pk_mul_f32 v[242:243], v[242:243], v[226:227]
	v_cvt_pk_bf16_f32 v234, v248, v249
	v_cvt_pk_bf16_f32 v235, v242, v243
	v_pk_mul_f32 v[248:249], v[244:245], v[224:225]
	v_pk_mul_f32 v[246:247], v[246:247], v[226:227]
	v_cvt_pk_bf16_f32 v236, v248, v249
	v_cvt_pk_bf16_f32 v237, v246, v247
	v_add_u32_e32 v170, 0x10000, v239
	v_add_u32_e32 v171, 0x14000, v239
	global_store_dwordx2 v170, v[234:235], s[68:69]
	global_store_dwordx2 v171, v[236:237], s[68:69]
	v_add_u32_e32 v149, 0x80000, v144
	v_add_u32_e32 v150, 0x88000, v144
	global_load_dwordx4 v[192:195], v149, s[72:73]
	global_load_dwordx4 v[196:199], v150, s[72:73]
	ds_write_b128 v152, v[76:79]
	ds_write_b128 v152, v[72:75] offset:16
	ds_read_b128 v[240:243], v153
	ds_read_b128 v[244:247], v153 offset:1152
	s_waitcnt lgkmcnt(4)
	s_waitcnt vmcnt(20)
	v_pk_add_f32 v[130:131], v[130:131], v[200:201]
	v_pk_add_f32 v[132:133], v[132:133], v[202:203]
	v_pk_add_f32 v[176:177], v[176:177], v[204:205]
	v_pk_add_f32 v[178:179], v[178:179], v[206:207]
	v_add_u32_e32 v180, 0x20200, v144
	v_add_u32_e32 v181, 0x28200, v144
	global_store_dwordx4 v180, v[130:133], s[72:73]
	global_store_dwordx4 v181, v[176:179], s[72:73]
	v_fmac_f32_e32 v232, v130, v130
	v_fmac_f32_e32 v232, v131, v131
	v_fmac_f32_e32 v232, v132, v132
	v_fmac_f32_e32 v232, v133, v133
	v_fmac_f32_e32 v233, v176, v176
	v_fmac_f32_e32 v233, v177, v177
	v_fmac_f32_e32 v233, v178, v178
	v_fmac_f32_e32 v233, v179, v179
	v_pk_mul_f32 v[248:249], v[130:131], v[228:229]
	v_pk_mul_f32 v[132:133], v[132:133], v[230:231]
	v_cvt_pk_bf16_f32 v234, v248, v249
	v_cvt_pk_bf16_f32 v235, v132, v133
	v_pk_mul_f32 v[248:249], v[176:177], v[228:229]
	v_pk_mul_f32 v[178:179], v[178:179], v[230:231]
	v_cvt_pk_bf16_f32 v236, v248, v249
	v_cvt_pk_bf16_f32 v237, v178, v179
	v_add_u32_e32 v170, 0x10100, v239
	v_add_u32_e32 v171, 0x14100, v239
	global_store_dwordx2 v170, v[234:235], s[68:69]
	global_store_dwordx2 v171, v[236:237], s[68:69]
	s_nop 0
	v_add_f32_dpp v232, v232, v232 quad_perm:[1,0,3,2] row_mask:0xf bank_mask:0xf
	v_add_f32_dpp v233, v233, v233 quad_perm:[1,0,3,2] row_mask:0xf bank_mask:0xf
	s_nop 0
	v_add_f32_dpp v232, v232, v232 quad_perm:[2,3,0,1] row_mask:0xf bank_mask:0xf
	v_add_f32_dpp v233, v233, v233 quad_perm:[2,3,0,1] row_mask:0xf bank_mask:0xf
	s_nop 0
	v_add_f32_dpp v232, v232, v232 row_half_mirror row_mask:0xf bank_mask:0xf
	v_add_f32_dpp v233, v233, v233 row_half_mirror row_mask:0xf bank_mask:0xf
	s_nop 0
	v_add_u32_e32 v151, 0x800, v238
	s_mov_b64 exec, s[38:39]
	global_store_dword v151, v232, s[68:69]
	global_store_dword v151, v233, s[68:69] offset:512
	s_mov_b64 exec, -1
	v_add_u32_e32 v145, 0x80200, v144
	v_add_u32_e32 v146, 0x88200, v144
	global_load_dwordx4 v[200:203], v145, s[72:73]
	global_load_dwordx4 v[204:207], v146, s[72:73]
	ds_write_b128 v152, v[68:71]
	ds_write_b128 v152, v[64:67] offset:16
	ds_read_b128 v[130:133], v153
	ds_read_b128 v[176:179], v153 offset:1152
	s_waitcnt lgkmcnt(4)
	s_waitcnt vmcnt(22)
	v_pk_add_f32 v[240:241], v[240:241], v[208:209]
	v_pk_add_f32 v[242:243], v[242:243], v[210:211]
	v_pk_add_f32 v[244:245], v[244:245], v[212:213]
	v_pk_add_f32 v[246:247], v[246:247], v[214:215]
	v_add_u32_e32 v180, 0x30000, v144
	v_add_u32_e32 v181, 0x38000, v144
	global_store_dwordx4 v180, v[240:243], s[72:73]
	global_store_dwordx4 v181, v[244:247], s[72:73]
	v_mul_f32_e32 v232, v240, v240
	v_fmac_f32_e32 v232, v241, v241
	v_fmac_f32_e32 v232, v242, v242
	v_fmac_f32_e32 v232, v243, v243
	v_mul_f32_e32 v233, v244, v244
	v_fmac_f32_e32 v233, v245, v245
	v_fmac_f32_e32 v233, v246, v246
	v_fmac_f32_e32 v233, v247, v247
	v_pk_mul_f32 v[248:249], v[240:241], v[224:225]
	v_pk_mul_f32 v[242:243], v[242:243], v[226:227]
	v_cvt_pk_bf16_f32 v234, v248, v249
	v_cvt_pk_bf16_f32 v235, v242, v243
	v_pk_mul_f32 v[248:249], v[244:245], v[224:225]
	v_pk_mul_f32 v[246:247], v[246:247], v[226:227]
	v_cvt_pk_bf16_f32 v236, v248, v249
	v_cvt_pk_bf16_f32 v237, v246, v247
	v_add_u32_e32 v170, 0x18000, v239
	v_add_u32_e32 v171, 0x1c000, v239
	global_store_dwordx2 v170, v[234:235], s[68:69]
	global_store_dwordx2 v171, v[236:237], s[68:69]
	v_add_u32_e32 v147, 0x90000, v144
	v_add_u32_e32 v148, 0x98000, v144
	global_load_dwordx4 v[208:211], v147, s[72:73]
	global_load_dwordx4 v[212:215], v148, s[72:73]
	ds_write_b128 v152, v[60:63]
	ds_write_b128 v152, v[56:59] offset:16
	ds_read_b128 v[240:243], v153
	ds_read_b128 v[244:247], v153 offset:1152
	s_waitcnt lgkmcnt(4)
	s_waitcnt vmcnt(20)
	v_pk_add_f32 v[130:131], v[130:131], v[216:217]
	v_pk_add_f32 v[132:133], v[132:133], v[218:219]
	v_pk_add_f32 v[176:177], v[176:177], v[220:221]
	v_pk_add_f32 v[178:179], v[178:179], v[222:223]
	v_add_u32_e32 v180, 0x30200, v144
	v_add_u32_e32 v181, 0x38200, v144
	global_store_dwordx4 v180, v[130:133], s[72:73]
	global_store_dwordx4 v181, v[176:179], s[72:73]
	v_fmac_f32_e32 v232, v130, v130
	v_fmac_f32_e32 v232, v131, v131
	v_fmac_f32_e32 v232, v132, v132
	v_fmac_f32_e32 v232, v133, v133
	v_fmac_f32_e32 v233, v176, v176
	v_fmac_f32_e32 v233, v177, v177
	v_fmac_f32_e32 v233, v178, v178
	v_fmac_f32_e32 v233, v179, v179
	v_pk_mul_f32 v[248:249], v[130:131], v[228:229]
	v_pk_mul_f32 v[132:133], v[132:133], v[230:231]
	v_cvt_pk_bf16_f32 v234, v248, v249
	v_cvt_pk_bf16_f32 v235, v132, v133
	v_pk_mul_f32 v[248:249], v[176:177], v[228:229]
	v_pk_mul_f32 v[178:179], v[178:179], v[230:231]
	v_cvt_pk_bf16_f32 v236, v248, v249
	v_cvt_pk_bf16_f32 v237, v178, v179
	v_add_u32_e32 v170, 0x18100, v239
	v_add_u32_e32 v171, 0x1c100, v239
	global_store_dwordx2 v170, v[234:235], s[68:69]
	global_store_dwordx2 v171, v[236:237], s[68:69]
	s_nop 0
	v_add_f32_dpp v232, v232, v232 quad_perm:[1,0,3,2] row_mask:0xf bank_mask:0xf
	v_add_f32_dpp v233, v233, v233 quad_perm:[1,0,3,2] row_mask:0xf bank_mask:0xf
	s_nop 0
	v_add_f32_dpp v232, v232, v232 quad_perm:[2,3,0,1] row_mask:0xf bank_mask:0xf
	v_add_f32_dpp v233, v233, v233 quad_perm:[2,3,0,1] row_mask:0xf bank_mask:0xf
	s_nop 0
	v_add_f32_dpp v232, v232, v232 row_half_mirror row_mask:0xf bank_mask:0xf
	v_add_f32_dpp v233, v233, v233 row_half_mirror row_mask:0xf bank_mask:0xf
	s_nop 0
	v_add_u32_e32 v151, 0xc00, v238
	s_mov_b64 exec, s[38:39]
	global_store_dword v151, v232, s[68:69]
	global_store_dword v151, v233, s[68:69] offset:512
	s_mov_b64 exec, -1
	v_add_u32_e32 v149, 0x90200, v144
	v_add_u32_e32 v150, 0x98200, v144
	global_load_dwordx4 v[216:219], v149, s[72:73]
	global_load_dwordx4 v[220:223], v150, s[72:73]
	ds_write_b128 v152, v[52:55]
	ds_write_b128 v152, v[48:51] offset:16
	ds_read_b128 v[130:133], v153
	ds_read_b128 v[176:179], v153 offset:1152
	s_waitcnt lgkmcnt(4)
	s_waitcnt vmcnt(22)
	v_pk_add_f32 v[240:241], v[240:241], v[192:193]
	v_pk_add_f32 v[242:243], v[242:243], v[194:195]
	v_pk_add_f32 v[244:245], v[244:245], v[196:197]
	v_pk_add_f32 v[246:247], v[246:247], v[198:199]
	v_add_u32_e32 v180, 0x80000, v144
	v_add_u32_e32 v181, 0x88000, v144
	global_store_dwordx4 v180, v[240:243], s[72:73]
	global_store_dwordx4 v181, v[244:247], s[72:73]
	v_mul_f32_e32 v232, v240, v240
	v_fmac_f32_e32 v232, v241, v241
	v_fmac_f32_e32 v232, v242, v242
	v_fmac_f32_e32 v232, v243, v243
	v_mul_f32_e32 v233, v244, v244
	v_fmac_f32_e32 v233, v245, v245
	v_fmac_f32_e32 v233, v246, v246
	v_fmac_f32_e32 v233, v247, v247
	v_pk_mul_f32 v[248:249], v[240:241], v[224:225]
	v_pk_mul_f32 v[242:243], v[242:243], v[226:227]
	v_cvt_pk_bf16_f32 v234, v248, v249
	v_cvt_pk_bf16_f32 v235, v242, v243
	v_pk_mul_f32 v[248:249], v[244:245], v[224:225]
	v_pk_mul_f32 v[246:247], v[246:247], v[226:227]
	v_cvt_pk_bf16_f32 v236, v248, v249
	v_cvt_pk_bf16_f32 v237, v246, v247
	v_add_u32_e32 v170, 0x40000, v239
	v_add_u32_e32 v171, 0x44000, v239
	global_store_dwordx2 v170, v[234:235], s[68:69]
	global_store_dwordx2 v171, v[236:237], s[68:69]
	v_add_u32_e32 v145, 0xa0000, v144
	v_add_u32_e32 v146, 0xa8000, v144
	global_load_dwordx4 v[192:195], v145, s[72:73]
	global_load_dwordx4 v[196:199], v146, s[72:73]
	ds_write_b128 v152, v[44:47]
	ds_write_b128 v152, v[40:43] offset:16
	ds_read_b128 v[240:243], v153
	ds_read_b128 v[244:247], v153 offset:1152
	s_waitcnt lgkmcnt(4)
	s_waitcnt vmcnt(20)
	v_pk_add_f32 v[130:131], v[130:131], v[200:201]
	v_pk_add_f32 v[132:133], v[132:133], v[202:203]
	v_pk_add_f32 v[176:177], v[176:177], v[204:205]
	v_pk_add_f32 v[178:179], v[178:179], v[206:207]
	v_add_u32_e32 v180, 0x80200, v144
	v_add_u32_e32 v181, 0x88200, v144
	global_store_dwordx4 v180, v[130:133], s[72:73]
	global_store_dwordx4 v181, v[176:179], s[72:73]
	v_fmac_f32_e32 v232, v130, v130
	v_fmac_f32_e32 v232, v131, v131
	v_fmac_f32_e32 v232, v132, v132
	v_fmac_f32_e32 v232, v133, v133
	v_fmac_f32_e32 v233, v176, v176
	v_fmac_f32_e32 v233, v177, v177
	v_fmac_f32_e32 v233, v178, v178
	v_fmac_f32_e32 v233, v179, v179
	v_pk_mul_f32 v[248:249], v[130:131], v[228:229]
	v_pk_mul_f32 v[132:133], v[132:133], v[230:231]
	v_cvt_pk_bf16_f32 v234, v248, v249
	v_cvt_pk_bf16_f32 v235, v132, v133
	v_pk_mul_f32 v[248:249], v[176:177], v[228:229]
	v_pk_mul_f32 v[178:179], v[178:179], v[230:231]
	v_cvt_pk_bf16_f32 v236, v248, v249
	v_cvt_pk_bf16_f32 v237, v178, v179
	v_add_u32_e32 v170, 0x40100, v239
	v_add_u32_e32 v171, 0x44100, v239
	global_store_dwordx2 v170, v[234:235], s[68:69]
	global_store_dwordx2 v171, v[236:237], s[68:69]
	s_nop 0
	v_add_f32_dpp v232, v232, v232 quad_perm:[1,0,3,2] row_mask:0xf bank_mask:0xf
	v_add_f32_dpp v233, v233, v233 quad_perm:[1,0,3,2] row_mask:0xf bank_mask:0xf
	s_nop 0
	v_add_f32_dpp v232, v232, v232 quad_perm:[2,3,0,1] row_mask:0xf bank_mask:0xf
	v_add_f32_dpp v233, v233, v233 quad_perm:[2,3,0,1] row_mask:0xf bank_mask:0xf
	s_nop 0
	v_add_f32_dpp v232, v232, v232 row_half_mirror row_mask:0xf bank_mask:0xf
	v_add_f32_dpp v233, v233, v233 row_half_mirror row_mask:0xf bank_mask:0xf
	s_nop 0
	v_add_u32_e32 v151, 0x2000, v238
	s_mov_b64 exec, s[38:39]
	global_store_dword v151, v232, s[68:69]
	global_store_dword v151, v233, s[68:69] offset:512
	s_mov_b64 exec, -1
	v_add_u32_e32 v147, 0xa0200, v144
	v_add_u32_e32 v148, 0xa8200, v144
	global_load_dwordx4 v[200:203], v147, s[72:73]
	global_load_dwordx4 v[204:207], v148, s[72:73]
	ds_write_b128 v152, v[36:39]
	ds_write_b128 v152, v[32:35] offset:16
	ds_read_b128 v[130:133], v153
	ds_read_b128 v[176:179], v153 offset:1152
	s_waitcnt lgkmcnt(4)
	s_waitcnt vmcnt(22)
	v_pk_add_f32 v[240:241], v[240:241], v[208:209]
	v_pk_add_f32 v[242:243], v[242:243], v[210:211]
	v_pk_add_f32 v[244:245], v[244:245], v[212:213]
	v_pk_add_f32 v[246:247], v[246:247], v[214:215]
	v_add_u32_e32 v180, 0x90000, v144
	v_add_u32_e32 v181, 0x98000, v144
	global_store_dwordx4 v180, v[240:243], s[72:73]
	global_store_dwordx4 v181, v[244:247], s[72:73]
	v_mul_f32_e32 v232, v240, v240
	v_fmac_f32_e32 v232, v241, v241
	v_fmac_f32_e32 v232, v242, v242
	v_fmac_f32_e32 v232, v243, v243
	v_mul_f32_e32 v233, v244, v244
	v_fmac_f32_e32 v233, v245, v245
	v_fmac_f32_e32 v233, v246, v246
	v_fmac_f32_e32 v233, v247, v247
	v_pk_mul_f32 v[248:249], v[240:241], v[224:225]
	v_pk_mul_f32 v[242:243], v[242:243], v[226:227]
	v_cvt_pk_bf16_f32 v234, v248, v249
	v_cvt_pk_bf16_f32 v235, v242, v243
	v_pk_mul_f32 v[248:249], v[244:245], v[224:225]
	v_pk_mul_f32 v[246:247], v[246:247], v[226:227]
	v_cvt_pk_bf16_f32 v236, v248, v249
	v_cvt_pk_bf16_f32 v237, v246, v247
	v_add_u32_e32 v170, 0x48000, v239
	v_add_u32_e32 v171, 0x4c000, v239
	global_store_dwordx2 v170, v[234:235], s[68:69]
	global_store_dwordx2 v171, v[236:237], s[68:69]
	v_add_u32_e32 v149, 0xb0000, v144
	v_add_u32_e32 v150, 0xb8000, v144
	global_load_dwordx4 v[208:211], v149, s[72:73]
	global_load_dwordx4 v[212:215], v150, s[72:73]
	ds_write_b128 v152, v[28:31]
	ds_write_b128 v152, v[24:27] offset:16
	ds_read_b128 v[240:243], v153
	ds_read_b128 v[244:247], v153 offset:1152
	s_waitcnt lgkmcnt(4)
	s_waitcnt vmcnt(20)
	v_pk_add_f32 v[130:131], v[130:131], v[216:217]
	v_pk_add_f32 v[132:133], v[132:133], v[218:219]
	v_pk_add_f32 v[176:177], v[176:177], v[220:221]
	v_pk_add_f32 v[178:179], v[178:179], v[222:223]
	v_add_u32_e32 v180, 0x90200, v144
	v_add_u32_e32 v181, 0x98200, v144
	global_store_dwordx4 v180, v[130:133], s[72:73]
	global_store_dwordx4 v181, v[176:179], s[72:73]
	v_fmac_f32_e32 v232, v130, v130
	v_fmac_f32_e32 v232, v131, v131
	v_fmac_f32_e32 v232, v132, v132
	v_fmac_f32_e32 v232, v133, v133
	v_fmac_f32_e32 v233, v176, v176
	v_fmac_f32_e32 v233, v177, v177
	v_fmac_f32_e32 v233, v178, v178
	v_fmac_f32_e32 v233, v179, v179
	v_pk_mul_f32 v[248:249], v[130:131], v[228:229]
	v_pk_mul_f32 v[132:133], v[132:133], v[230:231]
	v_cvt_pk_bf16_f32 v234, v248, v249
	v_cvt_pk_bf16_f32 v235, v132, v133
	v_pk_mul_f32 v[248:249], v[176:177], v[228:229]
	v_pk_mul_f32 v[178:179], v[178:179], v[230:231]
	v_cvt_pk_bf16_f32 v236, v248, v249
	v_cvt_pk_bf16_f32 v237, v178, v179
	v_add_u32_e32 v170, 0x48100, v239
	v_add_u32_e32 v171, 0x4c100, v239
	global_store_dwordx2 v170, v[234:235], s[68:69]
	global_store_dwordx2 v171, v[236:237], s[68:69]
	s_nop 0
	v_add_f32_dpp v232, v232, v232 quad_perm:[1,0,3,2] row_mask:0xf bank_mask:0xf
	v_add_f32_dpp v233, v233, v233 quad_perm:[1,0,3,2] row_mask:0xf bank_mask:0xf
	s_nop 0
	v_add_f32_dpp v232, v232, v232 quad_perm:[2,3,0,1] row_mask:0xf bank_mask:0xf
	v_add_f32_dpp v233, v233, v233 quad_perm:[2,3,0,1] row_mask:0xf bank_mask:0xf
	s_nop 0
	v_add_f32_dpp v232, v232, v232 row_half_mirror row_mask:0xf bank_mask:0xf
	v_add_f32_dpp v233, v233, v233 row_half_mirror row_mask:0xf bank_mask:0xf
	s_nop 0
	v_add_u32_e32 v151, 0x2400, v238
	s_mov_b64 exec, s[38:39]
	global_store_dword v151, v232, s[68:69]
	global_store_dword v151, v233, s[68:69] offset:512
	s_mov_b64 exec, -1
	v_add_u32_e32 v145, 0xb0200, v144
	v_add_u32_e32 v146, 0xb8200, v144
	global_load_dwordx4 v[216:219], v145, s[72:73]
	global_load_dwordx4 v[220:223], v146, s[72:73]
	ds_write_b128 v152, v[20:23]
	ds_write_b128 v152, v[16:19] offset:16
	ds_read_b128 v[130:133], v153
	ds_read_b128 v[176:179], v153 offset:1152
	s_waitcnt lgkmcnt(4)
	s_waitcnt vmcnt(22)
	v_pk_add_f32 v[240:241], v[240:241], v[192:193]
	v_pk_add_f32 v[242:243], v[242:243], v[194:195]
	v_pk_add_f32 v[244:245], v[244:245], v[196:197]
	v_pk_add_f32 v[246:247], v[246:247], v[198:199]
	v_add_u32_e32 v180, 0xa0000, v144
	v_add_u32_e32 v181, 0xa8000, v144
	global_store_dwordx4 v180, v[240:243], s[72:73]
	global_store_dwordx4 v181, v[244:247], s[72:73]
	v_mul_f32_e32 v232, v240, v240
	v_fmac_f32_e32 v232, v241, v241
	v_fmac_f32_e32 v232, v242, v242
	v_fmac_f32_e32 v232, v243, v243
	v_mul_f32_e32 v233, v244, v244
	v_fmac_f32_e32 v233, v245, v245
	v_fmac_f32_e32 v233, v246, v246
	v_fmac_f32_e32 v233, v247, v247
	v_pk_mul_f32 v[248:249], v[240:241], v[224:225]
	v_pk_mul_f32 v[242:243], v[242:243], v[226:227]
	v_cvt_pk_bf16_f32 v234, v248, v249
	v_cvt_pk_bf16_f32 v235, v242, v243
	v_pk_mul_f32 v[248:249], v[244:245], v[224:225]
	v_pk_mul_f32 v[246:247], v[246:247], v[226:227]
	v_cvt_pk_bf16_f32 v236, v248, v249
	v_cvt_pk_bf16_f32 v237, v246, v247
	v_add_u32_e32 v170, 0x50000, v239
	v_add_u32_e32 v171, 0x54000, v239
	global_store_dwordx2 v170, v[234:235], s[68:69]
	global_store_dwordx2 v171, v[236:237], s[68:69]
	ds_write_b128 v152, v[12:15]
	ds_write_b128 v152, v[8:11] offset:16
	ds_read_b128 v[240:243], v153
	ds_read_b128 v[244:247], v153 offset:1152
	s_waitcnt lgkmcnt(4)
	s_waitcnt vmcnt(18)
	v_pk_add_f32 v[130:131], v[130:131], v[200:201]
	v_pk_add_f32 v[132:133], v[132:133], v[202:203]
	v_pk_add_f32 v[176:177], v[176:177], v[204:205]
	v_pk_add_f32 v[178:179], v[178:179], v[206:207]
	v_add_u32_e32 v180, 0xa0200, v144
	v_add_u32_e32 v181, 0xa8200, v144
	global_store_dwordx4 v180, v[130:133], s[72:73]
	global_store_dwordx4 v181, v[176:179], s[72:73]
	v_fmac_f32_e32 v232, v130, v130
	v_fmac_f32_e32 v232, v131, v131
	v_fmac_f32_e32 v232, v132, v132
	v_fmac_f32_e32 v232, v133, v133
	v_fmac_f32_e32 v233, v176, v176
	v_fmac_f32_e32 v233, v177, v177
	v_fmac_f32_e32 v233, v178, v178
	v_fmac_f32_e32 v233, v179, v179
	v_pk_mul_f32 v[248:249], v[130:131], v[228:229]
	v_pk_mul_f32 v[132:133], v[132:133], v[230:231]
	v_cvt_pk_bf16_f32 v234, v248, v249
	v_cvt_pk_bf16_f32 v235, v132, v133
	v_pk_mul_f32 v[248:249], v[176:177], v[228:229]
	v_pk_mul_f32 v[178:179], v[178:179], v[230:231]
	v_cvt_pk_bf16_f32 v236, v248, v249
	v_cvt_pk_bf16_f32 v237, v178, v179
	v_add_u32_e32 v170, 0x50100, v239
	v_add_u32_e32 v171, 0x54100, v239
	global_store_dwordx2 v170, v[234:235], s[68:69]
	global_store_dwordx2 v171, v[236:237], s[68:69]
	s_nop 0
	v_add_f32_dpp v232, v232, v232 quad_perm:[1,0,3,2] row_mask:0xf bank_mask:0xf
	v_add_f32_dpp v233, v233, v233 quad_perm:[1,0,3,2] row_mask:0xf bank_mask:0xf
	s_nop 0
	v_add_f32_dpp v232, v232, v232 quad_perm:[2,3,0,1] row_mask:0xf bank_mask:0xf
	v_add_f32_dpp v233, v233, v233 quad_perm:[2,3,0,1] row_mask:0xf bank_mask:0xf
	s_nop 0
	v_add_f32_dpp v232, v232, v232 row_half_mirror row_mask:0xf bank_mask:0xf
	v_add_f32_dpp v233, v233, v233 row_half_mirror row_mask:0xf bank_mask:0xf
	s_nop 0
	v_add_u32_e32 v151, 0x2800, v238
	s_mov_b64 exec, s[38:39]
	global_store_dword v151, v232, s[68:69]
	global_store_dword v151, v233, s[68:69] offset:512
	s_mov_b64 exec, -1
	ds_write_b128 v152, v[4:7]
	ds_write_b128 v152, v[0:3] offset:16
	ds_read_b128 v[130:133], v153
	ds_read_b128 v[176:179], v153 offset:1152
	s_waitcnt lgkmcnt(4)
	s_waitcnt vmcnt(18)
	v_pk_add_f32 v[240:241], v[240:241], v[208:209]
	v_pk_add_f32 v[242:243], v[242:243], v[210:211]
	v_pk_add_f32 v[244:245], v[244:245], v[212:213]
	v_pk_add_f32 v[246:247], v[246:247], v[214:215]
	v_add_u32_e32 v180, 0xb0000, v144
	v_add_u32_e32 v181, 0xb8000, v144
	global_store_dwordx4 v180, v[240:243], s[72:73]
	global_store_dwordx4 v181, v[244:247], s[72:73]
	v_mul_f32_e32 v232, v240, v240
	v_fmac_f32_e32 v232, v241, v241
	v_fmac_f32_e32 v232, v242, v242
	v_fmac_f32_e32 v232, v243, v243
	v_mul_f32_e32 v233, v244, v244
	v_fmac_f32_e32 v233, v245, v245
	v_fmac_f32_e32 v233, v246, v246
	v_fmac_f32_e32 v233, v247, v247
	v_pk_mul_f32 v[248:249], v[240:241], v[224:225]
	v_pk_mul_f32 v[242:243], v[242:243], v[226:227]
	v_cvt_pk_bf16_f32 v234, v248, v249
	v_cvt_pk_bf16_f32 v235, v242, v243
	v_pk_mul_f32 v[248:249], v[244:245], v[224:225]
	v_pk_mul_f32 v[246:247], v[246:247], v[226:227]
	v_cvt_pk_bf16_f32 v236, v248, v249
	v_cvt_pk_bf16_f32 v237, v246, v247
	v_add_u32_e32 v170, 0x58000, v239
	v_add_u32_e32 v171, 0x5c000, v239
	global_store_dwordx2 v170, v[234:235], s[68:69]
	global_store_dwordx2 v171, v[236:237], s[68:69]
	s_waitcnt lgkmcnt(0)
	s_waitcnt vmcnt(14)
	v_pk_add_f32 v[130:131], v[130:131], v[216:217]
	v_pk_add_f32 v[132:133], v[132:133], v[218:219]
	v_pk_add_f32 v[176:177], v[176:177], v[220:221]
	v_pk_add_f32 v[178:179], v[178:179], v[222:223]
	v_add_u32_e32 v180, 0xb0200, v144
	v_add_u32_e32 v181, 0xb8200, v144
	global_store_dwordx4 v180, v[130:133], s[72:73]
	global_store_dwordx4 v181, v[176:179], s[72:73]
	v_fmac_f32_e32 v232, v130, v130
	v_fmac_f32_e32 v232, v131, v131
	v_fmac_f32_e32 v232, v132, v132
	v_fmac_f32_e32 v232, v133, v133
	v_fmac_f32_e32 v233, v176, v176
	v_fmac_f32_e32 v233, v177, v177
	v_fmac_f32_e32 v233, v178, v178
	v_fmac_f32_e32 v233, v179, v179
	v_pk_mul_f32 v[248:249], v[130:131], v[228:229]
	v_pk_mul_f32 v[132:133], v[132:133], v[230:231]
	v_cvt_pk_bf16_f32 v234, v248, v249
	v_cvt_pk_bf16_f32 v235, v132, v133
	v_pk_mul_f32 v[248:249], v[176:177], v[228:229]
	v_pk_mul_f32 v[178:179], v[178:179], v[230:231]
	v_cvt_pk_bf16_f32 v236, v248, v249
	v_cvt_pk_bf16_f32 v237, v178, v179
	v_add_u32_e32 v170, 0x58100, v239
	v_add_u32_e32 v171, 0x5c100, v239
	global_store_dwordx2 v170, v[234:235], s[68:69]
	global_store_dwordx2 v171, v[236:237], s[68:69]
	s_nop 0
	v_add_f32_dpp v232, v232, v232 quad_perm:[1,0,3,2] row_mask:0xf bank_mask:0xf
	v_add_f32_dpp v233, v233, v233 quad_perm:[1,0,3,2] row_mask:0xf bank_mask:0xf
	s_nop 0
	v_add_f32_dpp v232, v232, v232 quad_perm:[2,3,0,1] row_mask:0xf bank_mask:0xf
	v_add_f32_dpp v233, v233, v233 quad_perm:[2,3,0,1] row_mask:0xf bank_mask:0xf
	s_nop 0
	v_add_f32_dpp v232, v232, v232 row_half_mirror row_mask:0xf bank_mask:0xf
	v_add_f32_dpp v233, v233, v233 row_half_mirror row_mask:0xf bank_mask:0xf
	s_nop 0
	v_add_u32_e32 v151, 0x2c00, v238
	s_mov_b64 exec, s[38:39]
	global_store_dword v151, v232, s[68:69]
	global_store_dword v151, v233, s[68:69] offset:512
	s_mov_b64 exec, -1
	s_branch .Lres_join

.LBB0_678:
	v_lshrrev_b32_e32 v112, 6, v146
	v_bfe_u32 v114, v148, 5, 2
	v_lshl_add_u32 v112, v112, 2, v114
	v_mul_u32_u24_e32 v112, 2304, v112
	v_add_u32_e32 v112, 135424, v112
	v_and_b32_e32 v114, 15, v189
	v_mul_u32_u24_e32 v114, 144, v114
	v_lshrrev_b32_e32 v115, 4, v189
	v_lshl_add_u32 v114, v115, 4, v114
	v_add_u32_e32 v190, v112, v114
	v_lshrrev_b32_e32 v114, 3, v189
	v_and_b32_e32 v115, 7, v189
	v_mul_u32_u24_e32 v191, 144, v114
	v_lshl_add_u32 v191, v115, 4, v191
	v_add_u32_e32 v191, v112, v191
	v_and_b32_e32 v112, 0xfffffff0, v146
	v_add_u32_e32 v112, v112, v114
	v_lshl_add_u32 v112, s53, 8, v112
	v_and_b32_e32 v114, 0x60, v148
	v_lshl_add_u32 v114, v114, 1, 0
	v_lshl_add_u32 v114, v115, 3, v114
	v_lshl_add_u32 v114, s52, 8, v114
	v_mad_u32_u24 v144, v112, s6, v114
	s_lshl_b32 s21, s6, 4
	v_lshlrev_b32_e32 v144, 1, v144
	v_add_u32_e32 v145, s21, v144
	v_readlane_b32 s20, v254, 35
	v_lshl_add_u32 v112, s53, 8, v146
	v_lshlrev_b32_e32 v112, 2, v112
	s_and_b32 s21, s20, 1
	s_cmp_eq_u32 s21, 1
	s_cselect_b32 s21, 4, 8
	s_cmp_eq_u32 s78, s21
	s_cselect_b64 s[38:39], -1, 0
	s_cmp_eq_u32 s78, 0
	s_cselect_b64 vcc, -1, 0
	s_cmp_lg_u32 s20, 0
	s_cselect_b64 s[20:21], -1, 0
	s_and_b64 vcc, vcc, s[20:21]
	s_or_b64 s[38:39], s[38:39], vcc
	s_and_b64 vcc, exec, s[38:39]
	s_cbranch_vccz .Lg1e_noscale
	v_add_u32_e32 v114, 0x4308000, v112
	global_load_dword v192, v114, s[68:69]
	global_load_dword v194, v114, s[68:69] offset:64
	global_load_dword v196, v114, s[68:69] offset:128
	global_load_dword v198, v114, s[68:69] offset:192
	global_load_dword v200, v114, s[68:69] offset:512
	global_load_dword v202, v114, s[68:69] offset:576
	global_load_dword v204, v114, s[68:69] offset:640
	global_load_dword v206, v114, s[68:69] offset:704
	s_waitcnt vmcnt(0)
	v_pk_mul_f32 v[116:117], v[116:117], v[192:193] op_sel_hi:[1,0]
	v_pk_mul_f32 v[118:119], v[118:119], v[192:193] op_sel_hi:[1,0]
	v_pk_mul_f32 v[120:121], v[120:121], v[192:193] op_sel_hi:[1,0]
	v_pk_mul_f32 v[122:123], v[122:123], v[192:193] op_sel_hi:[1,0]
	v_pk_mul_f32 v[124:125], v[124:125], v[192:193] op_sel_hi:[1,0]
	v_pk_mul_f32 v[126:127], v[126:127], v[192:193] op_sel_hi:[1,0]
	v_pk_mul_f32 v[128:129], v[128:129], v[192:193] op_sel_hi:[1,0]
	v_pk_mul_f32 v[130:131], v[130:131], v[192:193] op_sel_hi:[1,0]
	v_pk_mul_f32 v[96:97], v[96:97], v[194:195] op_sel_hi:[1,0]
	v_pk_mul_f32 v[98:99], v[98:99], v[194:195] op_sel_hi:[1,0]
	v_pk_mul_f32 v[100:101], v[100:101], v[194:195] op_sel_hi:[1,0]
	v_pk_mul_f32 v[102:103], v[102:103], v[194:195] op_sel_hi:[1,0]
	v_pk_mul_f32 v[104:105], v[104:105], v[194:195] op_sel_hi:[1,0]
	v_pk_mul_f32 v[106:107], v[106:107], v[194:195] op_sel_hi:[1,0]
	v_pk_mul_f32 v[108:109], v[108:109], v[194:195] op_sel_hi:[1,0]
	v_pk_mul_f32 v[110:111], v[110:111], v[194:195] op_sel_hi:[1,0]
	v_pk_mul_f32 v[80:81], v[80:81], v[196:197] op_sel_hi:[1,0]
	v_pk_mul_f32 v[82:83], v[82:83], v[196:197] op_sel_hi:[1,0]
	v_pk_mul_f32 v[84:85], v[84:85], v[196:197] op_sel_hi:[1,0]
	v_pk_mul_f32 v[86:87], v[86:87], v[196:197] op_sel_hi:[1,0]
	v_pk_mul_f32 v[88:89], v[88:89], v[196:197] op_sel_hi:[1,0]
	v_pk_mul_f32 v[90:91], v[90:91], v[196:197] op_sel_hi:[1,0]
	v_pk_mul_f32 v[92:93], v[92:93], v[196:197] op_sel_hi:[1,0]
	v_pk_mul_f32 v[94:95], v[94:95], v[196:197] op_sel_hi:[1,0]
	v_pk_mul_f32 v[64:65], v[64:65], v[198:199] op_sel_hi:[1,0]
	v_pk_mul_f32 v[66:67], v[66:67], v[198:199] op_sel_hi:[1,0]
	v_pk_mul_f32 v[68:69], v[68:69], v[198:199] op_sel_hi:[1,0]
	v_pk_mul_f32 v[70:71], v[70:71], v[198:199] op_sel_hi:[1,0]
	v_pk_mul_f32 v[72:73], v[72:73], v[198:199] op_sel_hi:[1,0]
	v_pk_mul_f32 v[74:75], v[74:75], v[198:199] op_sel_hi:[1,0]
	v_pk_mul_f32 v[76:77], v[76:77], v[198:199] op_sel_hi:[1,0]
	v_pk_mul_f32 v[78:79], v[78:79], v[198:199] op_sel_hi:[1,0]
	v_pk_mul_f32 v[48:49], v[48:49], v[200:201] op_sel_hi:[1,0]
	v_pk_mul_f32 v[50:51], v[50:51], v[200:201] op_sel_hi:[1,0]
	v_pk_mul_f32 v[52:53], v[52:53], v[200:201] op_sel_hi:[1,0]
	v_pk_mul_f32 v[54:55], v[54:55], v[200:201] op_sel_hi:[1,0]
	v_pk_mul_f32 v[56:57], v[56:57], v[200:201] op_sel_hi:[1,0]
	v_pk_mul_f32 v[58:59], v[58:59], v[200:201] op_sel_hi:[1,0]
	v_pk_mul_f32 v[60:61], v[60:61], v[200:201] op_sel_hi:[1,0]
	v_pk_mul_f32 v[62:63], v[62:63], v[200:201] op_sel_hi:[1,0]
	v_pk_mul_f32 v[32:33], v[32:33], v[202:203] op_sel_hi:[1,0]
	v_pk_mul_f32 v[34:35], v[34:35], v[202:203] op_sel_hi:[1,0]
	v_pk_mul_f32 v[36:37], v[36:37], v[202:203] op_sel_hi:[1,0]
	v_pk_mul_f32 v[38:39], v[38:39], v[202:203] op_sel_hi:[1,0]
	v_pk_mul_f32 v[40:41], v[40:41], v[202:203] op_sel_hi:[1,0]
	v_pk_mul_f32 v[42:43], v[42:43], v[202:203] op_sel_hi:[1,0]
	v_pk_mul_f32 v[44:45], v[44:45], v[202:203] op_sel_hi:[1,0]
	v_pk_mul_f32 v[46:47], v[46:47], v[202:203] op_sel_hi:[1,0]
	v_pk_mul_f32 v[16:17], v[16:17], v[204:205] op_sel_hi:[1,0]
	v_pk_mul_f32 v[18:19], v[18:19], v[204:205] op_sel_hi:[1,0]
	v_pk_mul_f32 v[20:21], v[20:21], v[204:205] op_sel_hi:[1,0]
	v_pk_mul_f32 v[22:23], v[22:23], v[204:205] op_sel_hi:[1,0]
	v_pk_mul_f32 v[24:25], v[24:25], v[204:205] op_sel_hi:[1,0]
	v_pk_mul_f32 v[26:27], v[26:27], v[204:205] op_sel_hi:[1,0]
	v_pk_mul_f32 v[28:29], v[28:29], v[204:205] op_sel_hi:[1,0]
	v_pk_mul_f32 v[30:31], v[30:31], v[204:205] op_sel_hi:[1,0]
	v_pk_mul_f32 v[0:1], v[0:1], v[206:207] op_sel_hi:[1,0]
	v_pk_mul_f32 v[2:3], v[2:3], v[206:207] op_sel_hi:[1,0]
	v_pk_mul_f32 v[4:5], v[4:5], v[206:207] op_sel_hi:[1,0]
	v_pk_mul_f32 v[6:7], v[6:7], v[206:207] op_sel_hi:[1,0]
	v_pk_mul_f32 v[8:9], v[8:9], v[206:207] op_sel_hi:[1,0]
	v_pk_mul_f32 v[10:11], v[10:11], v[206:207] op_sel_hi:[1,0]
	v_pk_mul_f32 v[12:13], v[12:13], v[206:207] op_sel_hi:[1,0]
	v_pk_mul_f32 v[14:15], v[14:15], v[206:207] op_sel_hi:[1,0]
.Lg1e_noscale:
	s_lshl_b32 s21, s6, 4
	s_andn2_b64 vcc, exec, s[4:5]
	s_cbranch_vccnz .Lg1e_norelu
	v_max_f32_e32 v0, 0, v0
	v_max_f32_e32 v1, 0, v1
	v_max_f32_e32 v2, 0, v2
	v_max_f32_e32 v3, 0, v3
	v_max_f32_e32 v4, 0, v4
	v_max_f32_e32 v5, 0, v5
	v_max_f32_e32 v6, 0, v6
	v_max_f32_e32 v7, 0, v7
	v_max_f32_e32 v8, 0, v8
	v_max_f32_e32 v9, 0, v9
	v_max_f32_e32 v10, 0, v10
	v_max_f32_e32 v11, 0, v11
	v_max_f32_e32 v12, 0, v12
	v_max_f32_e32 v13, 0, v13
	v_max_f32_e32 v14, 0, v14
	v_max_f32_e32 v15, 0, v15
	v_max_f32_e32 v16, 0, v16
	v_max_f32_e32 v17, 0, v17
	v_max_f32_e32 v18, 0, v18
	v_max_f32_e32 v19, 0, v19
	v_max_f32_e32 v20, 0, v20
	v_max_f32_e32 v21, 0, v21
	v_max_f32_e32 v22, 0, v22
	v_max_f32_e32 v23, 0, v23
	v_max_f32_e32 v24, 0, v24
	v_max_f32_e32 v25, 0, v25
	v_max_f32_e32 v26, 0, v26
	v_max_f32_e32 v27, 0, v27
	v_max_f32_e32 v28, 0, v28
	v_max_f32_e32 v29, 0, v29
	v_max_f32_e32 v30, 0, v30
	v_max_f32_e32 v31, 0, v31
	v_max_f32_e32 v32, 0, v32
	v_max_f32_e32 v33, 0, v33
	v_max_f32_e32 v34, 0, v34
	v_max_f32_e32 v35, 0, v35
	v_max_f32_e32 v36, 0, v36
	v_max_f32_e32 v37, 0, v37
	v_max_f32_e32 v38, 0, v38
	v_max_f32_e32 v39, 0, v39
	v_max_f32_e32 v40, 0, v40
	v_max_f32_e32 v41, 0, v41
	v_max_f32_e32 v42, 0, v42
	v_max_f32_e32 v43, 0, v43
	v_max_f32_e32 v44, 0, v44
	v_max_f32_e32 v45, 0, v45
	v_max_f32_e32 v46, 0, v46
	v_max_f32_e32 v47, 0, v47
	v_max_f32_e32 v48, 0, v48
	v_max_f32_e32 v49, 0, v49
	v_max_f32_e32 v50, 0, v50
	v_max_f32_e32 v51, 0, v51
	v_max_f32_e32 v52, 0, v52
	v_max_f32_e32 v53, 0, v53
	v_max_f32_e32 v54, 0, v54
	v_max_f32_e32 v55, 0, v55
	v_max_f32_e32 v56, 0, v56
	v_max_f32_e32 v57, 0, v57
	v_max_f32_e32 v58, 0, v58
	v_max_f32_e32 v59, 0, v59
	v_max_f32_e32 v60, 0, v60
	v_max_f32_e32 v61, 0, v61
	v_max_f32_e32 v62, 0, v62
	v_max_f32_e32 v63, 0, v63
	v_max_f32_e32 v64, 0, v64
	v_max_f32_e32 v65, 0, v65
	v_max_f32_e32 v66, 0, v66
	v_max_f32_e32 v67, 0, v67
	v_max_f32_e32 v68, 0, v68
	v_max_f32_e32 v69, 0, v69
	v_max_f32_e32 v70, 0, v70
	v_max_f32_e32 v71, 0, v71
	v_max_f32_e32 v72, 0, v72
	v_max_f32_e32 v73, 0, v73
	v_max_f32_e32 v74, 0, v74
	v_max_f32_e32 v75, 0, v75
	v_max_f32_e32 v76, 0, v76
	v_max_f32_e32 v77, 0, v77
	v_max_f32_e32 v78, 0, v78
	v_max_f32_e32 v79, 0, v79
	v_max_f32_e32 v80, 0, v80
	v_max_f32_e32 v81, 0, v81
	v_max_f32_e32 v82, 0, v82
	v_max_f32_e32 v83, 0, v83
	v_max_f32_e32 v84, 0, v84
	v_max_f32_e32 v85, 0, v85
	v_max_f32_e32 v86, 0, v86
	v_max_f32_e32 v87, 0, v87
	v_max_f32_e32 v88, 0, v88
	v_max_f32_e32 v89, 0, v89
	v_max_f32_e32 v90, 0, v90
	v_max_f32_e32 v91, 0, v91
	v_max_f32_e32 v92, 0, v92
	v_max_f32_e32 v93, 0, v93
	v_max_f32_e32 v94, 0, v94
	v_max_f32_e32 v95, 0, v95
	v_max_f32_e32 v96, 0, v96
	v_max_f32_e32 v97, 0, v97
	v_max_f32_e32 v98, 0, v98
	v_max_f32_e32 v99, 0, v99
	v_max_f32_e32 v100, 0, v100
	v_max_f32_e32 v101, 0, v101
	v_max_f32_e32 v102, 0, v102
	v_max_f32_e32 v103, 0, v103
	v_max_f32_e32 v104, 0, v104
	v_max_f32_e32 v105, 0, v105
	v_max_f32_e32 v106, 0, v106
	v_max_f32_e32 v107, 0, v107
	v_max_f32_e32 v108, 0, v108
	v_max_f32_e32 v109, 0, v109
	v_max_f32_e32 v110, 0, v110
	v_max_f32_e32 v111, 0, v111
	v_max_f32_e32 v116, 0, v116
	v_max_f32_e32 v117, 0, v117
	v_max_f32_e32 v118, 0, v118
	v_max_f32_e32 v119, 0, v119
	v_max_f32_e32 v120, 0, v120
	v_max_f32_e32 v121, 0, v121
	v_max_f32_e32 v122, 0, v122
	v_max_f32_e32 v123, 0, v123
	v_max_f32_e32 v124, 0, v124
	v_max_f32_e32 v125, 0, v125
	v_max_f32_e32 v126, 0, v126
	v_max_f32_e32 v127, 0, v127
	v_max_f32_e32 v128, 0, v128
	v_max_f32_e32 v129, 0, v129
	v_max_f32_e32 v130, 0, v130
	v_max_f32_e32 v131, 0, v131
	v_pk_mul_f32 v[0:1], v[0:1], v[0:1]
	v_pk_mul_f32 v[2:3], v[2:3], v[2:3]
	v_pk_mul_f32 v[4:5], v[4:5], v[4:5]
	v_pk_mul_f32 v[6:7], v[6:7], v[6:7]
	v_pk_mul_f32 v[8:9], v[8:9], v[8:9]
	v_pk_mul_f32 v[10:11], v[10:11], v[10:11]
	v_pk_mul_f32 v[12:13], v[12:13], v[12:13]
	v_pk_mul_f32 v[14:15], v[14:15], v[14:15]
	v_pk_mul_f32 v[16:17], v[16:17], v[16:17]
	v_pk_mul_f32 v[18:19], v[18:19], v[18:19]
	v_pk_mul_f32 v[20:21], v[20:21], v[20:21]
	v_pk_mul_f32 v[22:23], v[22:23], v[22:23]
	v_pk_mul_f32 v[24:25], v[24:25], v[24:25]
	v_pk_mul_f32 v[26:27], v[26:27], v[26:27]
	v_pk_mul_f32 v[28:29], v[28:29], v[28:29]
	v_pk_mul_f32 v[30:31], v[30:31], v[30:31]
	v_pk_mul_f32 v[32:33], v[32:33], v[32:33]
	v_pk_mul_f32 v[34:35], v[34:35], v[34:35]
	v_pk_mul_f32 v[36:37], v[36:37], v[36:37]
	v_pk_mul_f32 v[38:39], v[38:39], v[38:39]
	v_pk_mul_f32 v[40:41], v[40:41], v[40:41]
	v_pk_mul_f32 v[42:43], v[42:43], v[42:43]
	v_pk_mul_f32 v[44:45], v[44:45], v[44:45]
	v_pk_mul_f32 v[46:47], v[46:47], v[46:47]
	v_pk_mul_f32 v[48:49], v[48:49], v[48:49]
	v_pk_mul_f32 v[50:51], v[50:51], v[50:51]
	v_pk_mul_f32 v[52:53], v[52:53], v[52:53]
	v_pk_mul_f32 v[54:55], v[54:55], v[54:55]
	v_pk_mul_f32 v[56:57], v[56:57], v[56:57]
	v_pk_mul_f32 v[58:59], v[58:59], v[58:59]
	v_pk_mul_f32 v[60:61], v[60:61], v[60:61]
	v_pk_mul_f32 v[62:63], v[62:63], v[62:63]
	v_pk_mul_f32 v[64:65], v[64:65], v[64:65]
	v_pk_mul_f32 v[66:67], v[66:67], v[66:67]
	v_pk_mul_f32 v[68:69], v[68:69], v[68:69]
	v_pk_mul_f32 v[70:71], v[70:71], v[70:71]
	v_pk_mul_f32 v[72:73], v[72:73], v[72:73]
	v_pk_mul_f32 v[74:75], v[74:75], v[74:75]
	v_pk_mul_f32 v[76:77], v[76:77], v[76:77]
	v_pk_mul_f32 v[78:79], v[78:79], v[78:79]
	v_pk_mul_f32 v[80:81], v[80:81], v[80:81]
	v_pk_mul_f32 v[82:83], v[82:83], v[82:83]
	v_pk_mul_f32 v[84:85], v[84:85], v[84:85]
	v_pk_mul_f32 v[86:87], v[86:87], v[86:87]
	v_pk_mul_f32 v[88:89], v[88:89], v[88:89]
	v_pk_mul_f32 v[90:91], v[90:91], v[90:91]
	v_pk_mul_f32 v[92:93], v[92:93], v[92:93]
	v_pk_mul_f32 v[94:95], v[94:95], v[94:95]
	v_pk_mul_f32 v[96:97], v[96:97], v[96:97]
	v_pk_mul_f32 v[98:99], v[98:99], v[98:99]
	v_pk_mul_f32 v[100:101], v[100:101], v[100:101]
	v_pk_mul_f32 v[102:103], v[102:103], v[102:103]
	v_pk_mul_f32 v[104:105], v[104:105], v[104:105]
	v_pk_mul_f32 v[106:107], v[106:107], v[106:107]
	v_pk_mul_f32 v[108:109], v[108:109], v[108:109]
	v_pk_mul_f32 v[110:111], v[110:111], v[110:111]
	v_pk_mul_f32 v[116:117], v[116:117], v[116:117]
	v_pk_mul_f32 v[118:119], v[118:119], v[118:119]
	v_pk_mul_f32 v[120:121], v[120:121], v[120:121]
	v_pk_mul_f32 v[122:123], v[122:123], v[122:123]
	v_pk_mul_f32 v[124:125], v[124:125], v[124:125]
	v_pk_mul_f32 v[126:127], v[126:127], v[126:127]
	v_pk_mul_f32 v[128:129], v[128:129], v[128:129]
	v_pk_mul_f32 v[130:131], v[130:131], v[130:131]
